# GEMM accumulator zeroing with v_mov_b64 (P1, P2h tail, P4 instances)
# speedup vs baseline: 1.0016x; 1.0008x over previous
; template <class Epi, class Sched, bool ALIGN_EPI = false, bool SP2 = false>
; __device__ __forceinline__ void gemm_phase(PG8_LAS unsigned char* lds, const Gemm g, const Sched& S, const Epi& E, const int wave_s) {
;     ...
;         const char* nA = has_next ? (const char*)g.A + (size_t)nxt.pm * tstepA : cA; const char* nB = has_next ? (const char*)g.Bt + (size_t)nxt.pn * tstepB : cB;
;         for (int t = 0; t < nt; t += 2) {
;             const bool last = (t == nt - 2);
;             const char* a1 = cA + (size_t)(t + 1) * kstep;
;             const char* a2 = last ? nA : cA + (size_t)(t + 2) * kstep; const char* b2 = last ? nB : cB + (size_t)(t + 2) * kstep;
;             const char* a3 = a2 + kstep; const char* b3 = b2 + kstep;
;     ...
; #pragma unroll
;         for (int a = 0; a < 2; ++a)
; #pragma unroll
;             for (int b = 0; b < 2; ++b)
; #pragma unroll
;                 for (int m = 0; m < 4; ++m)
; #pragma unroll
;                     for (int n = 0; n < 2; ++n) acc[a][b][m][n] = (f32x4){0.f, 0.f, 0.f, 0.f};
;         cur = nxt; cA = nA; cB = nB; ++ui;
.LBB0_268:
	s_ashr_i32 s83, s82, 31
	s_lshl_b64 s[72:73], s[82:83], 20
	s_add_u32 s84, s10, s72
	s_addc_u32 s85, s11, s73
	s_and_b64 s[72:73], s[38:39], exec
	s_cselect_b32 s26, s85, s41
	s_cselect_b32 s43, s84, s40
	s_ashr_i32 s81, s80, 31
	s_lshl_b64 s[72:73], s[80:81], 20
	s_add_u32 s86, s15, s72
	s_addc_u32 s87, s17, s73
	s_and_b64 s[72:73], s[38:39], exec
	s_cselect_b32 s72, s87, s91
	s_cselect_b32 s73, s86, s90
	s_add_u32 s40, s40, 0x80080
	s_addc_u32 s41, s41, 0
	s_add_u32 s81, s90, 0x100
	s_addc_u32 s83, s91, 0
	s_mov_b32 vcc_lo, -2
	v_mov_b64_e32 v[2:3], 0
	v_mov_b64_e32 v[4:5], 0
	v_mov_b64_e32 v[6:7], 0
	v_mov_b64_e32 v[8:9], 0
	v_mov_b64_e32 v[10:11], 0
	v_mov_b64_e32 v[12:13], 0
	v_mov_b64_e32 v[14:15], 0
	v_mov_b64_e32 v[16:17], 0
	v_mov_b64_e32 v[18:19], 0
	v_mov_b64_e32 v[20:21], 0
	v_mov_b64_e32 v[22:23], 0
	v_mov_b64_e32 v[24:25], 0
	v_mov_b64_e32 v[26:27], 0
	v_mov_b64_e32 v[28:29], 0
	v_mov_b64_e32 v[30:31], 0
	v_mov_b64_e32 v[32:33], 0
	v_mov_b64_e32 v[34:35], 0
	v_mov_b64_e32 v[36:37], 0
	v_mov_b64_e32 v[38:39], 0
	v_mov_b64_e32 v[40:41], 0
	v_mov_b64_e32 v[42:43], 0
	v_mov_b64_e32 v[44:45], 0
	v_mov_b64_e32 v[46:47], 0
	v_mov_b64_e32 v[48:49], 0
	v_mov_b64_e32 v[50:51], 0
	v_mov_b64_e32 v[52:53], 0
	v_mov_b64_e32 v[54:55], 0
	v_mov_b64_e32 v[56:57], 0
	v_mov_b64_e32 v[58:59], 0
	v_mov_b64_e32 v[60:61], 0
	v_mov_b64_e32 v[62:63], 0
	v_mov_b64_e32 v[64:65], 0
	v_mov_b64_e32 v[66:67], 0
	v_mov_b64_e32 v[68:69], 0
	v_mov_b64_e32 v[70:71], 0
	v_mov_b64_e32 v[72:73], 0
	v_mov_b64_e32 v[74:75], 0
	v_mov_b64_e32 v[76:77], 0
	v_mov_b64_e32 v[78:79], 0
	v_mov_b64_e32 v[80:81], 0
	v_mov_b64_e32 v[82:83], 0
	v_mov_b64_e32 v[84:85], 0
	v_mov_b64_e32 v[86:87], 0
	v_mov_b64_e32 v[88:89], 0
	v_mov_b64_e32 v[90:91], 0
	v_mov_b64_e32 v[92:93], 0
	v_mov_b64_e32 v[94:95], 0
	v_mov_b64_e32 v[96:97], 0
	v_mov_b64_e32 v[98:99], 0
	v_mov_b64_e32 v[100:101], 0
	v_mov_b64_e32 v[102:103], 0
	v_mov_b64_e32 v[104:105], 0
	v_mov_b64_e32 v[106:107], 0
	v_mov_b64_e32 v[108:109], 0
	v_mov_b64_e32 v[110:111], 0
	v_mov_b64_e32 v[112:113], 0
	v_mov_b64_e32 v[114:115], 0
	v_mov_b64_e32 v[116:117], 0
	v_mov_b64_e32 v[118:119], 0
	v_mov_b64_e32 v[120:121], 0
	v_mov_b64_e32 v[122:123], 0
	v_mov_b64_e32 v[124:125], 0
	v_mov_b64_e32 v[126:127], 0
	v_mov_b64_e32 v[128:129], 0

; template <class Epi, class Sched, bool ALIGN_EPI = false, bool SP2 = false>
; __device__ __forceinline__ void gemm_phase(PG8_LAS unsigned char* lds, const Gemm g, const Sched& S, const Epi& E, const int wave_s) {
;     ...
;         const char* nA = has_next ? (const char*)g.A + (size_t)nxt.pm * tstepA : cA; const char* nB = has_next ? (const char*)g.Bt + (size_t)nxt.pn * tstepB : cB;
;         for (int t = 0; t < nt; t += 2) {
;             const bool last = (t == nt - 2);
;             const char* a1 = cA + (size_t)(t + 1) * kstep;
;             const char* a2 = last ? nA : cA + (size_t)(t + 2) * kstep; const char* b2 = last ? nB : cB + (size_t)(t + 2) * kstep;
;             const char* a3 = a2 + kstep; const char* b3 = b2 + kstep;
;     ...
; #pragma unroll
;         for (int a = 0; a < 2; ++a)
; #pragma unroll
;             for (int b = 0; b < 2; ++b)
; #pragma unroll
;                 for (int m = 0; m < 4; ++m)
; #pragma unroll
;                     for (int n = 0; n < 2; ++n) acc[a][b][m][n] = (f32x4){0.f, 0.f, 0.f, 0.f};
;         cur = nxt; cA = nA; cB = nB; ++ui;
.LBB0_401:
	s_ashr_i32 s83, s82, 31
	s_lshl_b64 s[72:73], s[82:83], 20
	s_add_u32 s84, s10, s72
	s_addc_u32 s85, s11, s73
	s_and_b64 s[72:73], s[38:39], exec
	s_cselect_b32 s26, s85, s41
	s_cselect_b32 s72, s84, s40
	s_ashr_i32 s81, s80, 31
	s_lshl_b64 s[74:75], s[80:81], 20
	s_add_u32 s86, s15, s74
	s_addc_u32 s87, s17, s75
	s_and_b64 s[74:75], s[38:39], exec
	s_cselect_b32 s73, s87, s43
	s_cselect_b32 s81, s86, s42
	s_add_u32 s40, s40, 0x80080
	s_addc_u32 s41, s41, 0
	s_add_u32 s83, s42, 0x100
	s_addc_u32 vcc_lo, s43, 0
	s_mov_b32 vcc_hi, -2
	v_mov_b64_e32 v[2:3], 0
	v_mov_b64_e32 v[4:5], 0
	v_mov_b64_e32 v[6:7], 0
	v_mov_b64_e32 v[8:9], 0
	v_mov_b64_e32 v[10:11], 0
	v_mov_b64_e32 v[12:13], 0
	v_mov_b64_e32 v[14:15], 0
	v_mov_b64_e32 v[16:17], 0
	v_mov_b64_e32 v[18:19], 0
	v_mov_b64_e32 v[20:21], 0
	v_mov_b64_e32 v[22:23], 0
	v_mov_b64_e32 v[24:25], 0
	v_mov_b64_e32 v[26:27], 0
	v_mov_b64_e32 v[28:29], 0
	v_mov_b64_e32 v[30:31], 0
	v_mov_b64_e32 v[32:33], 0
	v_mov_b64_e32 v[34:35], 0
	v_mov_b64_e32 v[36:37], 0
	v_mov_b64_e32 v[38:39], 0
	v_mov_b64_e32 v[40:41], 0
	v_mov_b64_e32 v[42:43], 0
	v_mov_b64_e32 v[44:45], 0
	v_mov_b64_e32 v[46:47], 0
	v_mov_b64_e32 v[48:49], 0
	v_mov_b64_e32 v[50:51], 0
	v_mov_b64_e32 v[52:53], 0
	v_mov_b64_e32 v[54:55], 0
	v_mov_b64_e32 v[56:57], 0
	v_mov_b64_e32 v[58:59], 0
	v_mov_b64_e32 v[60:61], 0
	v_mov_b64_e32 v[62:63], 0
	v_mov_b64_e32 v[64:65], 0
	v_mov_b64_e32 v[66:67], 0
	v_mov_b64_e32 v[68:69], 0
	v_mov_b64_e32 v[70:71], 0
	v_mov_b64_e32 v[72:73], 0
	v_mov_b64_e32 v[74:75], 0
	v_mov_b64_e32 v[76:77], 0
	v_mov_b64_e32 v[78:79], 0
	v_mov_b64_e32 v[80:81], 0
	v_mov_b64_e32 v[82:83], 0
	v_mov_b64_e32 v[84:85], 0
	v_mov_b64_e32 v[86:87], 0
	v_mov_b64_e32 v[88:89], 0
	v_mov_b64_e32 v[90:91], 0
	v_mov_b64_e32 v[92:93], 0
	v_mov_b64_e32 v[94:95], 0
	v_mov_b64_e32 v[96:97], 0
	v_mov_b64_e32 v[98:99], 0
	v_mov_b64_e32 v[100:101], 0
	v_mov_b64_e32 v[102:103], 0
	v_mov_b64_e32 v[104:105], 0
	v_mov_b64_e32 v[106:107], 0
	v_mov_b64_e32 v[108:109], 0
	v_mov_b64_e32 v[110:111], 0
	v_mov_b64_e32 v[112:113], 0
	v_mov_b64_e32 v[114:115], 0
	v_mov_b64_e32 v[116:117], 0
	v_mov_b64_e32 v[118:119], 0
	v_mov_b64_e32 v[120:121], 0
	v_mov_b64_e32 v[122:123], 0
	v_mov_b64_e32 v[124:125], 0
	v_mov_b64_e32 v[126:127], 0
	v_mov_b64_e32 v[128:129], 0
	s_waitcnt vmcnt(0)

; template <class Epi, class Sched, bool ALIGN_EPI = false, bool SP2 = false>
; __device__ __forceinline__ void gemm_phase(PG8_LAS unsigned char* lds, const Gemm g, const Sched& S, const Epi& E, const int wave_s) {
;     ...
;         const char* nA = has_next ? (const char*)g.A + (size_t)nxt.pm * tstepA : cA; const char* nB = has_next ? (const char*)g.Bt + (size_t)nxt.pn * tstepB : cB;
;         for (int t = 0; t < nt; t += 2) {
;             const bool last = (t == nt - 2);
;             const char* a1 = cA + (size_t)(t + 1) * kstep;
;             const char* a2 = last ? nA : cA + (size_t)(t + 2) * kstep; const char* b2 = last ? nB : cB + (size_t)(t + 2) * kstep;
;             const char* a3 = a2 + kstep; const char* b3 = b2 + kstep;
;     ...
; #pragma unroll
;         for (int a = 0; a < 2; ++a)
; #pragma unroll
;             for (int b = 0; b < 2; ++b)
; #pragma unroll
;                 for (int m = 0; m < 4; ++m)
; #pragma unroll
;                     for (int n = 0; n < 2; ++n) acc[a][b][m][n] = (f32x4){0.f, 0.f, 0.f, 0.f};
;         cur = nxt; cA = nA; cB = nB; ++ui;
.LBB0_1157:
	s_ashr_i32 s55, s54, 31
	s_lshl_b64 s[56:57], s[54:55], 20
	s_add_u32 s56, s15, s56
	s_addc_u32 s57, s17, s57
	s_and_b64 s[60:61], s[36:37], exec
	s_cselect_b32 s55, s57, s39
	s_cselect_b32 s72, s56, s38
	s_ashr_i32 s53, s52, 31
	s_lshl_b64 s[60:61], s[52:53], 20
	s_add_u32 s60, s23, s60
	s_addc_u32 s61, s25, s61
	s_and_b64 s[62:63], s[36:37], exec
	s_cselect_b32 s53, s61, s83
	s_cselect_b32 s73, s60, s82
	s_add_u32 s38, s38, 0x80080
	s_addc_u32 s39, s39, 0
	s_add_u32 s90, s82, 0x100
	s_addc_u32 s91, s83, 0
	s_mov_b32 s74, -2
	v_mov_b64_e32 v[2:3], 0
	v_mov_b64_e32 v[4:5], 0
	v_mov_b64_e32 v[6:7], 0
	v_mov_b64_e32 v[8:9], 0
	v_mov_b64_e32 v[10:11], 0
	v_mov_b64_e32 v[12:13], 0
	v_mov_b64_e32 v[14:15], 0
	v_mov_b64_e32 v[16:17], 0
	v_mov_b64_e32 v[18:19], 0
	v_mov_b64_e32 v[20:21], 0
	v_mov_b64_e32 v[22:23], 0
	v_mov_b64_e32 v[24:25], 0
	v_mov_b64_e32 v[26:27], 0
	v_mov_b64_e32 v[28:29], 0
	v_mov_b64_e32 v[30:31], 0
	v_mov_b64_e32 v[32:33], 0
	v_mov_b64_e32 v[34:35], 0
	v_mov_b64_e32 v[36:37], 0
	v_mov_b64_e32 v[38:39], 0
	v_mov_b64_e32 v[40:41], 0
	v_mov_b64_e32 v[42:43], 0
	v_mov_b64_e32 v[44:45], 0
	v_mov_b64_e32 v[46:47], 0
	v_mov_b64_e32 v[48:49], 0
	v_mov_b64_e32 v[50:51], 0
	v_mov_b64_e32 v[52:53], 0
	v_mov_b64_e32 v[54:55], 0
	v_mov_b64_e32 v[56:57], 0
	v_mov_b64_e32 v[58:59], 0
	v_mov_b64_e32 v[60:61], 0
	v_mov_b64_e32 v[62:63], 0
	v_mov_b64_e32 v[64:65], 0
	v_mov_b64_e32 v[66:67], 0
	v_mov_b64_e32 v[68:69], 0
	v_mov_b64_e32 v[70:71], 0
	v_mov_b64_e32 v[72:73], 0
	v_mov_b64_e32 v[74:75], 0
	v_mov_b64_e32 v[76:77], 0
	v_mov_b64_e32 v[78:79], 0
	v_mov_b64_e32 v[80:81], 0
	v_mov_b64_e32 v[82:83], 0
	v_mov_b64_e32 v[84:85], 0
	v_mov_b64_e32 v[86:87], 0
	v_mov_b64_e32 v[88:89], 0
	v_mov_b64_e32 v[90:91], 0
	v_mov_b64_e32 v[92:93], 0
	v_mov_b64_e32 v[94:95], 0
	v_mov_b64_e32 v[96:97], 0
	v_mov_b64_e32 v[98:99], 0
	v_mov_b64_e32 v[100:101], 0
	v_mov_b64_e32 v[102:103], 0
	v_mov_b64_e32 v[104:105], 0
	v_mov_b64_e32 v[106:107], 0
	v_mov_b64_e32 v[108:109], 0
	v_mov_b64_e32 v[110:111], 0
	v_mov_b64_e32 v[112:113], 0
	v_mov_b64_e32 v[114:115], 0
	v_mov_b64_e32 v[116:117], 0
	v_mov_b64_e32 v[118:119], 0
	v_mov_b64_e32 v[120:121], 0
	v_mov_b64_e32 v[122:123], 0
	v_mov_b64_e32 v[124:125], 0
	v_mov_b64_e32 v[126:127], 0
	v_mov_b64_e32 v[128:129], 0
